# differential-attention unit epilogue: 16 dwordx2 output stores widened to 8 dwordx4 stores via v_permlane32_swap of the packed bf16 dwords (strategy 7.3)
# speedup vs baseline: 1.0197x; 1.0081x over previous
; DI void dattn_unit2(const bf16_t* __restrict__ Qg, const bf16_t* __restrict__ Kg, const bf16_t* __restrict__ Vg, bf16_t* __restrict__ Og,
;                     int ntiles, int wave_tiles, float lam, const float* __restrict__ gsub, lds_t* shm) {
;     ...
;   const float l0 = lrun[0] + __shfl_xor(lrun[0], 32), l1 = lrun[1] + __shfl_xor(lrun[1], 32);
;   const float i0 = 1.0f / l0, i1 = lam / l1;
;   float ssq = 0.f;
; #pragma unroll
;   for (int c = 0; c < NC; ++c)
; #pragma unroll
;     for (int i = 0; i < 16; ++i) { const float a = O[0][c][i] * i0 - O[1][c][i] * i1; O[0][c][i] = a; ssq += a * a; }
;   ssq += __shfl_xor(ssq, 32);
;   const float inv = rsqrtf(ssq * (1.0f / 128.0f) + RMS_EPS) * 0.8f;
.LBB0_414:
	ds_bpermute_b32 v128, v213, v201
	ds_bpermute_b32 v129, v213, v200
	s_lshl_b64 s[4:5], s[42:43], 1
	s_add_u32 s4, s35, s4
	s_addc_u32 s5, s46, s5
	s_waitcnt lgkmcnt(0)
	v_add_f32_e32 v128, v201, v128
	v_div_scale_f32 v130, s[6:7], v128, v128, 1.0
	v_rcp_f32_e32 v131, v130
	v_add_f32_e32 v129, v200, v129
	v_fma_f32 v132, -v130, v131, 1.0
	v_fmac_f32_e32 v131, v132, v131
	v_div_scale_f32 v132, vcc, 1.0, v128, 1.0
	v_mul_f32_e32 v133, v132, v131
	v_fma_f32 v134, -v130, v133, v132
	v_fmac_f32_e32 v133, v134, v131
	v_fma_f32 v130, -v130, v133, v132
	v_div_scale_f32 v132, s[6:7], v129, v129, v215
	v_rcp_f32_e32 v134, v132
	v_div_fmas_f32 v130, v130, v131, v133
	v_div_fixup_f32 v138, v130, v128, 1.0
	v_fma_f32 v128, -v132, v134, 1.0
	v_fmac_f32_e32 v134, v128, v134
	v_div_scale_f32 v128, vcc, v215, v129, v215
	v_mul_f32_e32 v130, v128, v134
	v_fma_f32 v131, -v132, v130, v128
	v_fmac_f32_e32 v130, v131, v134
	v_fma_f32 v128, -v132, v130, v128
	v_div_fmas_f32 v128, v128, v134, v130
	v_div_fixup_f32 v140, v128, v129, v215
	v_pk_mul_f32 v[28:29], v[28:29], v[140:141] op_sel_hi:[1,0]
	s_nop 0
	v_pk_fma_f32 v[128:129], v[12:13], v[138:139], v[28:29] op_sel_hi:[1,0,1] neg_lo:[0,0,1] neg_hi:[0,0,1]
	v_pk_mul_f32 v[12:13], v[30:31], v[140:141] op_sel_hi:[1,0]
	v_pk_mul_f32 v[134:135], v[128:129], v[128:129]
	v_pk_fma_f32 v[130:131], v[14:15], v[138:139], v[12:13] op_sel_hi:[1,0,1] neg_lo:[0,0,1] neg_hi:[0,0,1]
	v_mov_b32_e32 v139, v212
	v_pk_mul_f32 v[136:137], v[130:131], v[130:131]
	v_bfe_u32 v141, v139, 5, 1
	v_pk_mul_f32 v[12:13], v[112:113], v[140:141] op_sel_hi:[1,0]
	v_pk_mul_f32 v[28:29], v[80:81], v[140:141] op_sel_hi:[1,0]
	v_pk_fma_f32 v[112:113], v[96:97], v[138:139], v[12:13] op_sel_hi:[1,0,1] neg_lo:[0,0,1] neg_hi:[0,0,1]
	v_pk_mul_f32 v[12:13], v[114:115], v[140:141] op_sel_hi:[1,0]
	v_pk_fma_f32 v[80:81], v[64:65], v[138:139], v[28:29] op_sel_hi:[1,0,1] neg_lo:[0,0,1] neg_hi:[0,0,1]
	v_pk_fma_f32 v[132:133], v[98:99], v[138:139], v[12:13] op_sel_hi:[1,0,1] neg_lo:[0,0,1] neg_hi:[0,0,1]
	v_pk_mul_f32 v[12:13], v[116:117], v[140:141] op_sel_hi:[1,0]
	v_pk_mul_f32 v[28:29], v[82:83], v[140:141] op_sel_hi:[1,0]
	v_pk_fma_f32 v[114:115], v[100:101], v[138:139], v[12:13] op_sel_hi:[1,0,1] neg_lo:[0,0,1] neg_hi:[0,0,1]
	v_pk_mul_f32 v[12:13], v[118:119], v[140:141] op_sel_hi:[1,0]
	v_pk_fma_f32 v[82:83], v[66:67], v[138:139], v[28:29] op_sel_hi:[1,0,1] neg_lo:[0,0,1] neg_hi:[0,0,1]
	v_pk_mul_f32 v[28:29], v[84:85], v[140:141] op_sel_hi:[1,0]
	v_pk_fma_f32 v[118:119], v[102:103], v[138:139], v[12:13] op_sel_hi:[1,0,1] neg_lo:[0,0,1] neg_hi:[0,0,1]
	v_pk_mul_f32 v[12:13], v[120:121], v[140:141] op_sel_hi:[1,0]
	v_pk_fma_f32 v[84:85], v[68:69], v[138:139], v[28:29] op_sel_hi:[1,0,1] neg_lo:[0,0,1] neg_hi:[0,0,1]
	v_pk_mul_f32 v[68:69], v[88:89], v[140:141] op_sel_hi:[1,0]
	v_pk_fma_f32 v[116:117], v[104:105], v[138:139], v[12:13] op_sel_hi:[1,0,1] neg_lo:[0,0,1] neg_hi:[0,0,1]
	v_pk_mul_f32 v[12:13], v[122:123], v[140:141] op_sel_hi:[1,0]
	v_pk_fma_f32 v[88:89], v[72:73], v[138:139], v[68:69] op_sel_hi:[1,0,1] neg_lo:[0,0,1] neg_hi:[0,0,1]
	v_pk_mul_f32 v[68:69], v[90:91], v[140:141] op_sel_hi:[1,0]
	v_pk_fma_f32 v[122:123], v[106:107], v[138:139], v[12:13] op_sel_hi:[1,0,1] neg_lo:[0,0,1] neg_hi:[0,0,1]
	v_pk_mul_f32 v[12:13], v[124:125], v[140:141] op_sel_hi:[1,0]
	v_pk_fma_f32 v[90:91], v[74:75], v[138:139], v[68:69] op_sel_hi:[1,0,1] neg_lo:[0,0,1] neg_hi:[0,0,1]
	v_pk_mul_f32 v[68:69], v[92:93], v[140:141] op_sel_hi:[1,0]
	v_pk_mul_f32 v[48:49], v[48:49], v[140:141] op_sel_hi:[1,0]
	v_pk_mul_f32 v[142:143], v[112:113], v[112:113]
	v_pk_fma_f32 v[120:121], v[108:109], v[138:139], v[12:13] op_sel_hi:[1,0,1] neg_lo:[0,0,1] neg_hi:[0,0,1]
	v_pk_mul_f32 v[12:13], v[126:127], v[140:141] op_sel_hi:[1,0]
	v_pk_mul_f32 v[28:29], v[86:87], v[140:141] op_sel_hi:[1,0]
	v_pk_fma_f32 v[76:77], v[76:77], v[138:139], v[68:69] op_sel_hi:[1,0,1] neg_lo:[0,0,1] neg_hi:[0,0,1]
	v_pk_mul_f32 v[68:69], v[94:95], v[140:141] op_sel_hi:[1,0]
	v_pk_fma_f32 v[48:49], v[32:33], v[138:139], v[48:49] op_sel_hi:[1,0,1] neg_lo:[0,0,1] neg_hi:[0,0,1]
	v_pk_mul_f32 v[32:33], v[50:51], v[140:141] op_sel_hi:[1,0]
	v_pk_mul_f32 v[52:53], v[52:53], v[140:141] op_sel_hi:[1,0]
	v_pk_mul_f32 v[54:55], v[54:55], v[140:141] op_sel_hi:[1,0]
	v_pk_mul_f32 v[56:57], v[56:57], v[140:141] op_sel_hi:[1,0]
	v_pk_mul_f32 v[58:59], v[58:59], v[140:141] op_sel_hi:[1,0]
	v_pk_mul_f32 v[60:61], v[60:61], v[140:141] op_sel_hi:[1,0]
	v_pk_mul_f32 v[62:63], v[62:63], v[140:141] op_sel_hi:[1,0]
	v_pk_mul_f32 v[16:17], v[16:17], v[140:141] op_sel_hi:[1,0]
	v_pk_mul_f32 v[18:19], v[18:19], v[140:141] op_sel_hi:[1,0]
	v_pk_mul_f32 v[20:21], v[20:21], v[140:141] op_sel_hi:[1,0]
	v_pk_mul_f32 v[22:23], v[22:23], v[140:141] op_sel_hi:[1,0]
	v_pk_mul_f32 v[24:25], v[24:25], v[140:141] op_sel_hi:[1,0]
	v_pk_mul_f32 v[26:27], v[26:27], v[140:141] op_sel_hi:[1,0]
	v_lshlrev_b32_e32 v168, 4, v141
	v_pk_mul_f32 v[144:145], v[132:133], v[132:133]
	v_pk_fma_f32 v[108:109], v[110:111], v[138:139], v[12:13] op_sel_hi:[1,0,1] neg_lo:[0,0,1] neg_hi:[0,0,1]
	v_pk_fma_f32 v[86:87], v[70:71], v[138:139], v[28:29] op_sel_hi:[1,0,1] neg_lo:[0,0,1] neg_hi:[0,0,1]
	v_pk_fma_f32 v[78:79], v[78:79], v[138:139], v[68:69] op_sel_hi:[1,0,1] neg_lo:[0,0,1] neg_hi:[0,0,1]
	v_pk_fma_f32 v[50:51], v[34:35], v[138:139], v[32:33] op_sel_hi:[1,0,1] neg_lo:[0,0,1] neg_hi:[0,0,1]
	v_pk_fma_f32 v[36:37], v[36:37], v[138:139], v[52:53] op_sel_hi:[1,0,1] neg_lo:[0,0,1] neg_hi:[0,0,1]
	v_pk_fma_f32 v[38:39], v[38:39], v[138:139], v[54:55] op_sel_hi:[1,0,1] neg_lo:[0,0,1] neg_hi:[0,0,1]
; DI int tidx() { int t = threadIdx.x; asm volatile("" : "+v"(t)); return t; }
; DI void dattn_unit2(const bf16_t* __restrict__ Qg, const bf16_t* __restrict__ Kg, const bf16_t* __restrict__ Vg, bf16_t* __restrict__ Og,
;                     int ntiles, int wave_tiles, float lam, const float* __restrict__ gsub, lds_t* shm) {
;     ...
;   for (int c = 0; c < NC; ++c)
; #pragma unroll
;     for (int i = 0; i < 16; ++i) { const float a = O[0][c][i] * i0 - O[1][c][i] * i1; O[0][c][i] = a; ssq += a * a; }
;   ssq += __shfl_xor(ssq, 32);
;   const float inv = rsqrtf(ssq * (1.0f / 128.0f) + RMS_EPS) * 0.8f;
;   const int lane_f = tidx() & 63, h_f = lane_f >> 5;
;   const unsigned ooff = ((unsigned)(lane_f & 31) * (unsigned)LD + 4u * h_f) * 2u;
	v_pk_fma_f32 v[40:41], v[40:41], v[138:139], v[56:57] op_sel_hi:[1,0,1] neg_lo:[0,0,1] neg_hi:[0,0,1]
	v_pk_fma_f32 v[42:43], v[42:43], v[138:139], v[58:59] op_sel_hi:[1,0,1] neg_lo:[0,0,1] neg_hi:[0,0,1]
	v_pk_fma_f32 v[44:45], v[44:45], v[138:139], v[60:61] op_sel_hi:[1,0,1] neg_lo:[0,0,1] neg_hi:[0,0,1]
	v_pk_fma_f32 v[46:47], v[46:47], v[138:139], v[62:63] op_sel_hi:[1,0,1] neg_lo:[0,0,1] neg_hi:[0,0,1]
	v_pk_fma_f32 v[0:1], v[0:1], v[138:139], v[16:17] op_sel_hi:[1,0,1] neg_lo:[0,0,1] neg_hi:[0,0,1]
	v_pk_fma_f32 v[2:3], v[2:3], v[138:139], v[18:19] op_sel_hi:[1,0,1] neg_lo:[0,0,1] neg_hi:[0,0,1]
	v_pk_fma_f32 v[4:5], v[4:5], v[138:139], v[20:21] op_sel_hi:[1,0,1] neg_lo:[0,0,1] neg_hi:[0,0,1]
	v_pk_fma_f32 v[6:7], v[6:7], v[138:139], v[22:23] op_sel_hi:[1,0,1] neg_lo:[0,0,1] neg_hi:[0,0,1]
	v_pk_fma_f32 v[8:9], v[8:9], v[138:139], v[24:25] op_sel_hi:[1,0,1] neg_lo:[0,0,1] neg_hi:[0,0,1]
	v_pk_fma_f32 v[10:11], v[10:11], v[138:139], v[26:27] op_sel_hi:[1,0,1] neg_lo:[0,0,1] neg_hi:[0,0,1]
	v_add_f32_e32 v138, v142, v143
	global_load_dwordx4 v[100:103], v168, s[38:39]
	global_load_dwordx4 v[96:99], v168, s[38:39] offset:32
	v_add_f32_e32 v138, v144, v138
	v_pk_mul_f32 v[146:147], v[114:115], v[114:115]
	v_add_f32_e32 v138, v145, v138
	v_add_f32_e32 v138, v146, v138
	v_pk_mul_f32 v[148:149], v[118:119], v[118:119]
	v_add_f32_e32 v138, v147, v138
	v_add_f32_e32 v138, v148, v138
	v_pk_mul_f32 v[150:151], v[116:117], v[116:117]
	v_add_f32_e32 v138, v149, v138
	global_load_dwordx4 v[104:107], v168, s[38:39] offset:64
	global_load_dwordx4 v[12:15], v168, s[38:39] offset:96
	v_add_f32_e32 v138, v150, v138
	v_pk_mul_f32 v[152:153], v[122:123], v[122:123]
	v_add_f32_e32 v138, v151, v138
	v_add_f32_e32 v138, v152, v138
	v_pk_mul_f32 v[124:125], v[120:121], v[120:121]
	v_add_f32_e32 v138, v153, v138
	v_add_f32_e32 v124, v124, v138
	v_pk_mul_f32 v[110:111], v[108:109], v[108:109]
	v_add_f32_e32 v124, v125, v124
	v_add_f32_e32 v110, v110, v124
	v_pk_mul_f32 v[126:127], v[80:81], v[80:81]
	v_add_f32_e32 v110, v111, v110
	v_add_f32_e32 v110, v126, v110
	v_pk_mul_f32 v[154:155], v[82:83], v[82:83]
	v_add_f32_e32 v110, v127, v110
	v_add_f32_e32 v110, v154, v110
	v_pk_mul_f32 v[156:157], v[84:85], v[84:85]
	v_add_f32_e32 v110, v155, v110
	v_add_f32_e32 v110, v156, v110
	v_pk_mul_f32 v[158:159], v[86:87], v[86:87]
	v_add_f32_e32 v110, v157, v110
	v_add_f32_e32 v110, v158, v110
	v_pk_mul_f32 v[160:161], v[88:89], v[88:89]
	v_add_f32_e32 v110, v159, v110
	v_add_f32_e32 v110, v160, v110
	v_pk_mul_f32 v[162:163], v[90:91], v[90:91]
	v_add_f32_e32 v110, v161, v110
	v_add_f32_e32 v110, v162, v110
	v_pk_mul_f32 v[92:93], v[76:77], v[76:77]
	v_add_f32_e32 v110, v163, v110
	v_add_f32_e32 v92, v92, v110
	v_pk_mul_f32 v[94:95], v[78:79], v[78:79]
	v_add_f32_e32 v92, v93, v92
	v_add_f32_e32 v92, v94, v92
	v_pk_mul_f32 v[164:165], v[48:49], v[48:49]
	v_add_f32_e32 v92, v95, v92
	v_add_f32_e32 v92, v164, v92
	v_pk_mul_f32 v[166:167], v[50:51], v[50:51]
	v_add_f32_e32 v92, v165, v92
	v_add_f32_e32 v92, v166, v92
	v_pk_mul_f32 v[52:53], v[36:37], v[36:37]
	v_add_f32_e32 v92, v167, v92
	v_add_f32_e32 v52, v52, v92
	v_pk_mul_f32 v[54:55], v[38:39], v[38:39]
	v_add_f32_e32 v52, v53, v52
	v_add_f32_e32 v52, v54, v52
	v_pk_mul_f32 v[56:57], v[40:41], v[40:41]
	v_add_f32_e32 v52, v55, v52
	v_add_f32_e32 v52, v56, v52
	v_pk_mul_f32 v[58:59], v[42:43], v[42:43]
	v_add_f32_e32 v52, v57, v52
	v_add_f32_e32 v52, v58, v52
	v_pk_mul_f32 v[60:61], v[44:45], v[44:45]
	v_add_f32_e32 v52, v59, v52
	v_add_f32_e32 v52, v60, v52
	v_pk_mul_f32 v[62:63], v[46:47], v[46:47]
	v_add_f32_e32 v52, v61, v52
	v_add_f32_e32 v52, v62, v52
	v_pk_mul_f32 v[16:17], v[0:1], v[0:1]
	v_add_f32_e32 v52, v63, v52
	v_add_f32_e32 v16, v16, v52
	v_pk_mul_f32 v[18:19], v[2:3], v[2:3]
	v_add_f32_e32 v16, v17, v16
	v_add_f32_e32 v16, v18, v16
	v_pk_mul_f32 v[20:21], v[4:5], v[4:5]
	v_add_f32_e32 v16, v19, v16
	v_add_f32_e32 v16, v20, v16
	v_pk_mul_f32 v[22:23], v[6:7], v[6:7]
	v_add_f32_e32 v16, v21, v16
	v_add_f32_e32 v16, v22, v16
	v_pk_mul_f32 v[24:25], v[8:9], v[8:9]
	v_add_f32_e32 v16, v23, v16
	v_add_f32_e32 v16, v24, v16
	v_pk_mul_f32 v[26:27], v[10:11], v[10:11]
	v_add_f32_e32 v16, v25, v16
	v_add_f32_e32 v16, v26, v16
	v_add_f32_e32 v16, v27, v16
	v_add_f32_e32 v16, v134, v16
	v_add_f32_e32 v16, v135, v16
	v_add_f32_e32 v16, v136, v16
	v_add_f32_e32 v16, v137, v16
	ds_bpermute_b32 v17, v213, v16
	global_load_dwordx4 v[64:67], v168, s[38:39] offset:128
	global_load_dwordx4 v[28:31], v168, s[38:39] offset:160
	global_load_dwordx4 v[72:75], v168, s[38:39] offset:192
	global_load_dwordx4 v[68:71], v168, s[38:39] offset:224
	v_lshlrev_b32_e32 v18, 11, v139
	v_and_b32_e32 v18, 0xf800, v18
	s_waitcnt lgkmcnt(0)
	v_add_f32_e32 v16, v16, v17
	v_fmamk_f32 v16, v16, 0x3c000000, v216
	v_mul_f32_e32 v17, 0x4b800000, v16
	v_cmp_gt_f32_e32 vcc, s23, v16
	v_lshl_or_b32 v110, v141, 3, v18
	v_mbcnt_lo_u32_b32 v250, -1, 0
	v_mbcnt_hi_u32_b32 v250, -1, v250
	v_and_b32_e32 v250, 32, v250
	v_lshrrev_b32_e32 v250, 2, v250
	v_add_u32_e32 v110, v110, v250
	global_load_dwordx4 v[32:35], v168, s[38:39] offset:256
	global_load_dwordx4 v[18:21], v168, s[38:39] offset:288
	v_cndmask_b32_e32 v16, v16, v17, vcc
	v_rsq_f32_e32 v16, v16
	global_load_dwordx4 v[22:25], v168, s[38:39] offset:320
	global_load_dwordx4 v[52:55], v168, s[38:39] offset:352
	global_load_dwordx4 v[56:59], v168, s[38:39] offset:384
	global_load_dwordx4 v[60:63], v168, s[38:39] offset:416
	v_mul_f32_e32 v17, 0x45800000, v16
	v_cndmask_b32_e32 v16, v16, v17, vcc
	v_mul_f32_e32 v16, 0x3f4ccccd, v16
	v_pk_mul_f32 v[26:27], v[112:113], v[16:17] op_sel_hi:[1,0]
	v_pk_mul_f32 v[92:93], v[132:133], v[16:17] op_sel_hi:[1,0]
	s_waitcnt vmcnt(0)
; DI unsigned pk2(float lo, float hi) { bf2_t v = __builtin_convertvector((f32x2){lo, hi}, bf2_t); return __builtin_bit_cast(unsigned, v); }
; DI void dattn_unit2(const bf16_t* __restrict__ Qg, const bf16_t* __restrict__ Kg, const bf16_t* __restrict__ Vg, bf16_t* __restrict__ Og,
;                     int ntiles, int wave_tiles, float lam, const float* __restrict__ gsub, lds_t* shm) {
;     ...
; #pragma unroll
;   for (int c = 0; c < NC; ++c)
; #pragma unroll
;     for (int g4 = 0; g4 < 4; ++g4) {
;       const int dv0 = 32 * c + 8 * g4; f32x4 o;
; #pragma unroll
;       for (int e = 0; e < 4; ++e) o[e] = O[0][c][4 * g4 + e] * inv;
;       o = o * gld<f32x4>(gsub + dv0, 16u * h_f);
;       u32x2 w; w.x = pk2(o[0], o[1]); w.y = pk2(o[2], o[3]);
;       gst<u32x2>(Og + dv0, ooff, w);
;     }
	v_pk_mul_f32 v[26:27], v[100:101], v[26:27]
	v_pk_mul_f32 v[92:93], v[102:103], v[92:93]
	v_cvt_pk_bf16_f32 v218, v26, v27
	v_cvt_pk_bf16_f32 v219, v92, v93
	v_pk_mul_f32 v[26:27], v[114:115], v[16:17] op_sel_hi:[1,0]
	v_pk_mul_f32 v[92:93], v[118:119], v[16:17] op_sel_hi:[1,0]
	v_pk_mul_f32 v[26:27], v[96:97], v[26:27]
	v_pk_mul_f32 v[92:93], v[98:99], v[92:93]
	v_cvt_pk_bf16_f32 v220, v26, v27
	v_cvt_pk_bf16_f32 v221, v92, v93
	s_nop 1
	v_permlane32_swap_b32_e32 v218, v220
	v_permlane32_swap_b32_e32 v219, v221
	global_store_dwordx4 v110, v[218:221], s[4:5]
	v_pk_mul_f32 v[26:27], v[116:117], v[16:17] op_sel_hi:[1,0]
	v_pk_mul_f32 v[92:93], v[122:123], v[16:17] op_sel_hi:[1,0]
	v_pk_mul_f32 v[26:27], v[104:105], v[26:27]
	v_pk_mul_f32 v[92:93], v[106:107], v[92:93]
	v_cvt_pk_bf16_f32 v222, v26, v27
	v_cvt_pk_bf16_f32 v223, v92, v93
	v_pk_mul_f32 v[26:27], v[120:121], v[16:17] op_sel_hi:[1,0]
	global_load_dwordx4 v[92:95], v168, s[38:39] offset:448
	v_pk_mul_f32 v[96:97], v[108:109], v[16:17] op_sel_hi:[1,0]
	v_pk_mul_f32 v[12:13], v[12:13], v[26:27]
	v_pk_mul_f32 v[14:15], v[14:15], v[96:97]
	v_cvt_pk_bf16_f32 v224, v12, v13
	v_cvt_pk_bf16_f32 v225, v14, v15
	s_nop 1
	v_permlane32_swap_b32_e32 v222, v224
	v_permlane32_swap_b32_e32 v223, v225
	global_store_dwordx4 v110, v[222:225], s[4:5] offset:32
	global_load_dwordx4 v[12:15], v168, s[38:39] offset:480
	v_pk_mul_f32 v[26:27], v[80:81], v[16:17] op_sel_hi:[1,0]
	v_pk_mul_f32 v[80:81], v[82:83], v[16:17] op_sel_hi:[1,0]
	v_pk_mul_f32 v[0:1], v[0:1], v[16:17] op_sel_hi:[1,0]
	v_pk_mul_f32 v[2:3], v[2:3], v[16:17] op_sel_hi:[1,0]
	s_andn2_b64 vcc, exec, s[40:41]
	v_pk_mul_f32 v[66:67], v[66:67], v[80:81]
	v_pk_mul_f32 v[26:27], v[64:65], v[26:27]
	v_pk_mul_f32 v[64:65], v[86:87], v[16:17] op_sel_hi:[1,0]
	v_cvt_pk_bf16_f32 v226, v26, v27
	v_cvt_pk_bf16_f32 v227, v66, v67
	v_pk_mul_f32 v[26:27], v[84:85], v[16:17] op_sel_hi:[1,0]
	v_pk_mul_f32 v[30:31], v[30:31], v[64:65]
	v_pk_mul_f32 v[26:27], v[28:29], v[26:27]
	v_pk_mul_f32 v[28:29], v[90:91], v[16:17] op_sel_hi:[1,0]
	v_cvt_pk_bf16_f32 v228, v26, v27
	v_cvt_pk_bf16_f32 v229, v30, v31
	s_nop 1
	v_permlane32_swap_b32_e32 v226, v228
	v_permlane32_swap_b32_e32 v227, v229
	global_store_dwordx4 v110, v[226:229], s[4:5] offset:64
	v_pk_mul_f32 v[26:27], v[88:89], v[16:17] op_sel_hi:[1,0]
	v_pk_mul_f32 v[28:29], v[74:75], v[28:29]
	v_pk_mul_f32 v[26:27], v[72:73], v[26:27]
	v_pk_mul_f32 v[2:3], v[58:59], v[2:3]
	v_cvt_pk_bf16_f32 v230, v26, v27
	v_cvt_pk_bf16_f32 v231, v28, v29
	v_pk_mul_f32 v[26:27], v[76:77], v[16:17] op_sel_hi:[1,0]
	v_pk_mul_f32 v[28:29], v[78:79], v[16:17] op_sel_hi:[1,0]
	v_pk_mul_f32 v[26:27], v[68:69], v[26:27]
	v_pk_mul_f32 v[28:29], v[70:71], v[28:29]
	v_cvt_pk_bf16_f32 v232, v26, v27
	v_cvt_pk_bf16_f32 v233, v28, v29
	s_nop 1
	v_permlane32_swap_b32_e32 v230, v232
	v_permlane32_swap_b32_e32 v231, v233
	global_store_dwordx4 v110, v[230:233], s[4:5] offset:96
	v_pk_mul_f32 v[26:27], v[48:49], v[16:17] op_sel_hi:[1,0]
	v_pk_mul_f32 v[28:29], v[50:51], v[16:17] op_sel_hi:[1,0]
	v_pk_mul_f32 v[26:27], v[32:33], v[26:27]
	v_pk_mul_f32 v[28:29], v[34:35], v[28:29]
	v_pk_mul_f32 v[0:1], v[56:57], v[0:1]
	v_cvt_pk_bf16_f32 v234, v26, v27
	v_cvt_pk_bf16_f32 v235, v28, v29
	v_cvt_pk_bf16_f32 v242, v0, v1
	v_cvt_pk_bf16_f32 v243, v2, v3
	v_pk_mul_f32 v[26:27], v[36:37], v[16:17] op_sel_hi:[1,0]
	v_pk_mul_f32 v[28:29], v[38:39], v[16:17] op_sel_hi:[1,0]
	v_pk_mul_f32 v[0:1], v[4:5], v[16:17] op_sel_hi:[1,0]
	v_pk_mul_f32 v[2:3], v[6:7], v[16:17] op_sel_hi:[1,0]
	v_pk_mul_f32 v[20:21], v[20:21], v[28:29]
	v_pk_mul_f32 v[18:19], v[18:19], v[26:27]
	v_pk_mul_f32 v[2:3], v[62:63], v[2:3]
	v_pk_mul_f32 v[0:1], v[60:61], v[0:1]
	v_cvt_pk_bf16_f32 v236, v18, v19
	v_cvt_pk_bf16_f32 v237, v20, v21
	v_cvt_pk_bf16_f32 v244, v0, v1
	v_cvt_pk_bf16_f32 v245, v2, v3
	s_nop 1
	v_permlane32_swap_b32_e32 v234, v236
	v_permlane32_swap_b32_e32 v235, v237
	global_store_dwordx4 v110, v[234:237], s[4:5] offset:128
	v_pk_mul_f32 v[18:19], v[40:41], v[16:17] op_sel_hi:[1,0]
	v_pk_mul_f32 v[20:21], v[42:43], v[16:17] op_sel_hi:[1,0]
	s_nop 1
	v_permlane32_swap_b32_e32 v242, v244
	v_permlane32_swap_b32_e32 v243, v245
	global_store_dwordx4 v110, v[242:245], s[4:5] offset:192
	v_pk_mul_f32 v[0:1], v[8:9], v[16:17] op_sel_hi:[1,0]
	v_pk_mul_f32 v[2:3], v[10:11], v[16:17] op_sel_hi:[1,0]
	v_pk_mul_f32 v[20:21], v[24:25], v[20:21]
	v_pk_mul_f32 v[18:19], v[22:23], v[18:19]
	s_waitcnt vmcnt(6)
	v_pk_mul_f32 v[2:3], v[94:95], v[2:3]
	v_pk_mul_f32 v[0:1], v[92:93], v[0:1]
	v_cvt_pk_bf16_f32 v238, v18, v19
	v_cvt_pk_bf16_f32 v239, v20, v21
	v_cvt_pk_bf16_f32 v246, v0, v1
	v_cvt_pk_bf16_f32 v247, v2, v3
	v_pk_mul_f32 v[18:19], v[44:45], v[16:17] op_sel_hi:[1,0]
	v_pk_mul_f32 v[20:21], v[46:47], v[16:17] op_sel_hi:[1,0]
	v_pk_mul_f32 v[0:1], v[128:129], v[16:17] op_sel_hi:[1,0]
	v_pk_mul_f32 v[2:3], v[130:131], v[16:17] op_sel_hi:[1,0]
	v_pk_mul_f32 v[20:21], v[54:55], v[20:21]
	v_pk_mul_f32 v[18:19], v[52:53], v[18:19]
	s_waitcnt vmcnt(4)
	v_pk_mul_f32 v[2:3], v[14:15], v[2:3]
	v_pk_mul_f32 v[0:1], v[12:13], v[0:1]
	v_cvt_pk_bf16_f32 v240, v18, v19
	v_cvt_pk_bf16_f32 v241, v20, v21
	v_cvt_pk_bf16_f32 v248, v0, v1
	v_cvt_pk_bf16_f32 v249, v2, v3
	s_nop 1
	v_permlane32_swap_b32_e32 v238, v240
	v_permlane32_swap_b32_e32 v239, v241
	global_store_dwordx4 v110, v[238:241], s[4:5] offset:160
	s_nop 1
	v_permlane32_swap_b32_e32 v246, v248
	v_permlane32_swap_b32_e32 v247, v249
	global_store_dwordx4 v110, v[246:249], s[4:5] offset:224
	s_mov_b64 s[4:5], 0
	s_cbranch_vccz .LBB0_406
